# byte-phase pin: P0/P1 code (K-loop head) back to 0 mod 8 as in the unmodified file (two 4-byte pads; later phases keep their placement)
# baseline (speedup 1.0000x reference)
.LBB0_5:
	s_or_b64 exec, exec, s[2:3]
	s_load_dwordx16 s[80:95], s[0:1], 0x0
	v_mbcnt_lo_u32_b32 v0, -1, 0
	v_mbcnt_hi_u32_b32 v231, -1, v0
	v_lshlrev_b32_e32 v246, 4, v231
	s_lshl_b32 s33, s63, 10
	v_mov_b32_e32 v0, v246
	s_waitcnt lgkmcnt(0)
	v_lshlrev_b32_e32 v232, 2, v231
	global_load_dword v233, v232, s[10:11]
	global_load_dword v234, v232, s[12:13]
	global_load_dword v235, v232, s[10:11] offset:256
	global_load_dword v240, v232, s[12:13] offset:256
	s_nop 0
	s_add_u32 s0, s90, s33
	s_barrier
	s_addc_u32 s1, s91, 0
	v_ashrrev_i32_e32 v1, 31, v0
	s_add_i32 s76, s33, 0
	v_lshl_add_u64 v[0:1], s[0:1], 0, v[0:1]
	s_add_i32 s0, s76, 0x20000
	s_mov_b32 s1, m0
	s_mov_b32 m0, s0
	s_nop 0
	global_load_lds_dwordx4 v[0:1], off
	s_mov_b32 m0, s1
	s_sub_i32 s0, s99, s98
	s_add_u32 s2, s66, 0x4000
	s_addc_u32 s3, s67, 0
	v_writelane_b32 v254, s2, 3
	s_mov_b32 s55, 0
	s_cmp_gt_i32 s0, 1
	v_writelane_b32 v254, s3, 4
	s_mov_b32 s0, 0
	s_cbranch_scc0 .LBB0_10
	v_mbcnt_lo_u32_b32 v0, -1, 0
	v_mbcnt_hi_u32_b32 v0, -1, v0
	v_readlane_b32 s0, v254, 2
	v_sub_u32_e32 v0, 0, v0
	s_nop 0
	v_cmp_eq_u32_e32 vcc, s0, v0
	s_getreg_b32 s0, hwreg(HW_REG_XCC_ID, 0, 4)
	s_and_b32 s55, s0, 15
	s_and_saveexec_b64 s[0:1], vcc
	s_cbranch_execz .LBB0_9
	s_mov_b64 s[2:3], exec
	v_mbcnt_lo_u32_b32 v0, s2, 0
	v_mbcnt_hi_u32_b32 v0, s3, v0
	v_cmp_eq_u32_e32 vcc, 0, v0
	s_and_b64 s[4:5], exec, vcc
	s_mov_b64 exec, s[4:5]
	s_cbranch_execz .LBB0_9
	s_bcnt1_i32_b64 s2, s[2:3]
	s_lshl_b32 s4, s55, 8
	v_mov_b32_e32 v1, s2
	v_readlane_b32 s2, v254, 3
	v_mov_b32_e32 v0, s4
	v_readlane_b32 s3, v254, 4
	s_nop 4
	global_atomic_add v0, v1, s[2:3] offset:1024

.LBB0_291:
	s_nop 0
	s_add_u32 s56, s64, 0x2000000
	s_addc_u32 s57, s65, 0
	s_cmp_lt_i32 s98, 3
	s_cselect_b64 s[0:1], -1, 0
	s_cmp_gt_i32 s99, 2
	s_cselect_b64 s[2:3], -1, 0
	s_and_b64 s[0:1], s[0:1], s[2:3]
	s_andn2_b64 vcc, exec, s[0:1]
	s_cbranch_vccnz .LBB0_518
	s_getreg_b32 s77, hwreg(HW_REG_XCC_ID, 0, 4)
	v_mbcnt_lo_u32_b32 v0, -1, 0
	v_mbcnt_hi_u32_b32 v0, -1, v0
	v_readlane_b32 s0, v254, 2
	v_sub_u32_e32 v0, 0, v0
	s_nop 0
	v_cmp_eq_u32_e32 vcc, s0, v0
	s_and_saveexec_b64 s[0:1], vcc
	s_cbranch_execnz .LBB0_474
	s_or_b64 exec, exec, s[0:1]
	s_cmp_lg_u32 s63, 3
	s_cbranch_scc0 .LBB0_475
